# speedup vs baseline: 1.0020x; 1.0020x over previous
; #define LAS __attribute__((address_space(3)))
; #define MFMA32(a_, b_, c_) __builtin_amdgcn_mfma_f32_32x32x16_bf16((a_), (b_), (c_), 0, 0, 0)
; __device__ __forceinline__ int crow(int reg, int h) { return (reg & 3) + 8 * (reg >> 2) + 4 * h; }
; #define WAVE_FENCE() asm volatile("s_waitcnt lgkmcnt(0)" ::: "memory")
; template <bool OUT>
; __device__ __forceinline__ void ssm_fast(KArgs ap, int l, LAS unsigned char* lds, const Ctx cx) {
;     ...
;         for (int sc = 0; sc < 4; ++sc) {
;             const size_t tk = tok0 + sc * 32;
;             const bf16x8 uf = *(const bf16x8*)(z + (tk + r) * DIN + ZS + g * 16 + 8 * hh);
;             bf16_t uv[2][4];
;             if (OUT) {
; #pragma unroll
;                 for (int tbk = 0; tbk < 2; ++tbk)
; #pragma unroll
;                     for (int j = 0; j < 4; ++j) uv[tbk][j] = z[(tk + tbk * 16 + 4 * (lane >> 4) + j) * DIN + ZS + g * 16 + (lane & 15)];
;             }
;             WAVE_FENCE();
; #pragma unroll
;             for (int nb = 0; nb < 4; ++nb) { f32x16 c;
; #pragma unroll
;                 for (int i = 0; i < 16; ++i) c[i] = 0.f;
;                 c = MFMA32(uf, bt[nb], c);
; #pragma unroll
;                 for (int i = 0; i < 16; ++i) *(LAS float*)(BU + (crow(i, hh) * 128 + nb * 32 + r) * 4) = c[i]; }
.Lssmc_have_u:
	v_lshl_add_u64 v[174:175], v[0:1], 0, s[58:59]
	v_or_b32_e32 v0, s8, v100
	v_or_b32_e32 v1, s8, v106
	v_or_b32_e32 v2, s8, v108
	v_or_b32_e32 v3, s8, v110
	v_or_b32_e32 v4, s8, v112
	v_or_b32_e32 v5, s8, v114
	v_or_b32_e32 v6, s8, v116
	v_or_b32_e32 v7, s8, v118
	v_mad_u64_u32 v[32:33], s[10:11], v0, s12, v[140:141]
	v_mad_u64_u32 v[34:35], s[10:11], v1, s12, v[140:141]
	v_mad_u64_u32 v[36:37], s[10:11], v2, s12, v[140:141]
	v_mad_u64_u32 v[38:39], s[10:11], v3, s12, v[140:141]
	v_mad_u64_u32 v[40:41], s[10:11], v4, s12, v[140:141]
	v_mad_u64_u32 v[42:43], s[10:11], v5, s12, v[140:141]
	v_mad_u64_u32 v[44:45], s[10:11], v6, s12, v[140:141]
	v_mad_u64_u32 v[46:47], s[10:11], v7, s12, v[140:141]
	v_mad_i32_i24 v33, s9, v198, v33
	v_mad_i32_i24 v35, s9, v198, v35
	v_mad_i32_i24 v37, s9, v198, v37
	v_mad_i32_i24 v39, s9, v198, v39
	v_mad_i32_i24 v41, s9, v198, v41
	v_mad_i32_i24 v43, s9, v198, v43
	v_mad_i32_i24 v45, s9, v198, v45
	v_mad_i32_i24 v47, s9, v198, v47
	global_load_ushort v144, v[32:33], off offset:2560
	global_load_ushort v131, v[34:35], off offset:2560
	global_load_ushort v129, v[36:37], off offset:2560
	global_load_ushort v127, v[38:39], off offset:2560
	global_load_ushort v125, v[40:41], off offset:2560
	global_load_ushort v123, v[42:43], off offset:2560
	global_load_ushort v121, v[44:45], off offset:2560
	global_load_ushort v119, v[46:47], off offset:2560
	s_waitcnt lgkmcnt(0)
	s_movk_i32 s10, 0xc000
	s_mov_b32 s11, 3
	s_cmp_lg_u32 s1, 0
	s_cbranch_scc1 .Lssmc_skipwait
	s_waitcnt vmcnt(8)
.Lssmc_skipwait:
	v_mfma_f32_32x32x16_bf16 v[0:15], v[170:173], v[80:83], 0
	v_mfma_f32_32x32x16_bf16 v[16:31], v[170:173], v[64:67], 0
	v_mfma_f32_32x32x16_bf16 v[32:47], v[170:173], v[68:71], 0
	v_mfma_f32_32x32x16_bf16 v[48:63], v[170:173], v[72:75], 0
	s_nop 9
	s_cmp_eq_u32 s1, 3
	s_cbranch_scc1 .Lssmc_no_pf
	global_load_dwordx4 v[170:173], v[174:175], off offset:2560
